# S5 pass C: loop-invariant LDS write addresses computed once per item instead of per block
# baseline (speedup 1.0000x reference)
; __device__ __forceinline__ void s5_lambda(const Args& a, int g, int p, float& lbr, float& lbi, float& qr, float& qi) {
;     const float lr = a.in[I_LRE][g * 64 + p], li = a.in[I_LIM][g * 64 + p], dt = expf(a.in[I_LDT][g]);
;     const float mag = expf(lr * dt), ang = li * dt;
;     lbr = mag * cosf(ang); lbi = mag * sinf(ang);
;     const float den = lr * lr + li * li;
;     qr = ((lbr - 1.f) * lr + lbi * li) / den; qi = (lbi * lr - (lbr - 1.f) * li) / den;
; }
; __device__ __forceinline__ void s5_consts(const Args& a, int g, int lane, S5Consts& c) {
;     ...
;         const int ps = r + 32 * (nb >> 1); const float qr = (nb >> 1) ? q1r : q0r, qi = (nb >> 1) ? q1i : q0i;
;         const float* br = a.in[I_BRE] + (size_t)(g * 64 + ps) * 16 + 8 * hf; const float* bi = a.in[I_BIM] + (size_t)(g * 64 + ps) * 16 + 8 * hf;
;         float v[8];
; #pragma unroll
;         for (int j = 0; j < 8; ++j) v[j] = (nb & 1) ? (qr * bi[j] + qi * br[j]) : (qr * br[j] - qi * bi[j]);
.LBB0_891:
	s_or_b64 exec, exec, s[2:3]
	s_waitcnt vmcnt(0)
	v_mul_f32_e32 v19, v4, v10
	v_mul_f32_e32 v20, 0x3fb8aa3b, v19
	v_fma_f32 v21, v19, s26, -v20
	v_rndne_f32_e32 v22, v20
	v_fmac_f32_e32 v21, 0x32a5705f, v19
	v_sub_f32_e32 v20, v20, v22
	v_add_f32_e32 v20, v20, v21
	v_exp_f32_e32 v20, v20
	v_cvt_i32_f32_e32 v21, v22
	s_lshl_b32 s2, s12, 5
	s_lshl_b32 s3, s12, 10
	v_cmp_ngt_f32_e32 vcc, s27, v19
	v_ldexp_f32 v20, v20, v21
	s_and_b32 s2, s2, 0xffffe000
	s_and_b32 s3, s3, 0x1c00
	v_cndmask_b32_e32 v20, 0, v20, vcc
	v_cmp_nlt_f32_e32 vcc, s28, v19
	s_or_b32 s7, s2, s3
	s_and_b32 s2, s19, 0xffffe000
	v_cndmask_b32_e32 v24, v164, v20, vcc
	v_mul_f32_e32 v20, v16, v16
	v_or_b32_e32 v22, s2, v121
	s_and_b32 s2, s24, 0x1c00
	v_fmamk_f32 v21, v20, 0x37d75334, v161
	v_or_b32_e32 v130, s2, v22
	v_fmaak_f32 v21, v20, v21, 0x3d2aabf7
	v_fmamk_f32 v22, v20, 0xb94c1982, v162
	v_fmaak_f32 v21, v20, v21, 0xbf000004
	v_fmaak_f32 v22, v20, v22, 0xbe2aaa9d
	v_fma_f32 v21, v20, v21, 1.0
	v_mul_f32_e32 v20, v20, v22
	v_mul_f32_e32 v4, v8, v4
	v_fmac_f32_e32 v16, v16, v20
	v_mul_f32_e32 v20, 0x3fb8aa3b, v4
	v_fma_f32 v22, v4, s26, -v20
	v_rndne_f32_e32 v23, v20
	v_fmac_f32_e32 v22, 0x32a5705f, v4
	v_sub_f32_e32 v20, v20, v23
	v_add_f32_e32 v20, v20, v22
	v_exp_f32_e32 v20, v20
	v_cvt_i32_f32_e32 v22, v23
	v_lshlrev_b32_e32 v19, 30, v17
	v_and_b32_e32 v17, 1, v17
	v_cmp_eq_u32_e32 vcc, 0, v17
	v_xor_b32_e32 v3, v3, v2
	v_mov_b32_e32 v17, v8
	v_cndmask_b32_e64 v16, -v16, v21, vcc
	v_bitop3_b32 v19, v19, v16, s54 bitop3:0x6c
	v_ldexp_f32 v16, v20, v22
	v_cmp_ngt_f32_e32 vcc, s27, v4
	v_mov_b32_e32 v21, v0
	v_lshlrev_b32_e32 v112, 6, v1
	v_cndmask_b32_e32 v16, 0, v16, vcc
	v_cmp_nlt_f32_e32 vcc, s28, v4
	v_lshlrev_b32_e32 v4, 30, v9
	v_and_b32_e32 v4, 0x80000000, v4
	v_xor_b32_e32 v3, v3, v4
	v_and_b32_e32 v4, 1, v9
	v_mul_f32_e32 v9, v7, v7
	v_cndmask_b32_e32 v22, v164, v16, vcc
	v_fmamk_f32 v16, v9, 0xb94c1982, v162
	v_fmaak_f32 v16, v9, v16, 0xbe2aaa9d
	v_mul_f32_e32 v16, v9, v16
	v_fmac_f32_e32 v7, v7, v16
	v_fmamk_f32 v16, v9, 0x37d75334, v161
	v_fmaak_f32 v16, v9, v16, 0x3d2aabf7
	v_fmaak_f32 v16, v9, v16, 0xbf000004
	v_fma_f32 v9, v9, v16, 1.0
	v_cmp_eq_u32_e32 vcc, 0, v4
	v_readlane_b32 s56, v254, 43
	v_readlane_b32 s64, v254, 51
	v_cndmask_b32_e32 v4, v9, v7, vcc
	v_xor_b32_e32 v3, v3, v4
	v_cmp_class_f32_e64 vcc, v2, s53
	v_mul_f32_e32 v4, v5, v5
	v_fmamk_f32 v7, v4, 0xb94c1982, v162
	v_cndmask_b32_e32 v2, v168, v3, vcc
	v_mul_f32_e32 v16, v22, v2
	v_lshlrev_b32_e32 v2, 30, v6
	v_and_b32_e32 v3, 1, v6
	v_fmamk_f32 v6, v4, 0x37d75334, v161
	v_fmaak_f32 v6, v4, v6, 0x3d2aabf7
	v_fmaak_f32 v6, v4, v6, 0xbf000004
	v_fmaak_f32 v7, v4, v7, 0xbe2aaa9d
	v_fma_f32 v6, v4, v6, 1.0
	v_mul_f32_e32 v4, v4, v7
	v_fmac_f32_e32 v5, v5, v4
	v_cmp_eq_u32_e64 s[2:3], 0, v3
	v_readlane_b32 s65, v254, 52
	v_readlane_b32 s66, v254, 53
	v_cndmask_b32_e64 v3, -v5, v6, s[2:3]
	v_bitop3_b32 v2, v2, v3, s54 bitop3:0x6c
	v_cndmask_b32_e32 v6, v168, v2, vcc
	v_fma_f32 v20, v22, v6, -1.0
	v_pk_mul_f32 v[2:3], v[8:9], v[16:17] op_sel_hi:[0,1]
	v_pk_mul_f32 v[4:5], v[0:1], v[20:21] op_sel_hi:[0,1]
	v_sub_f32_e32 v17, v2, v4
	v_add_f32_e32 v25, v3, v5
	v_div_scale_f32 v2, s[2:3], v25, v25, v17
	v_rcp_f32_e32 v34, v2
	v_cmp_class_f32_e64 s[2:3], v13, s53
	v_mul_f32_e32 v37, v22, v6
	v_mov_b32_e32 v9, v0
	v_fma_f32 v3, -v2, v34, 1.0
	v_fmac_f32_e32 v34, v3, v34
	v_div_scale_f32 v3, vcc, v17, v25, v17
	v_cndmask_b32_e64 v35, v168, v19, s[2:3]
	v_mul_f32_e32 v19, v3, v34
	v_fma_f32 v4, -v2, v19, v3
	v_fmac_f32_e32 v19, v4, v34
	v_lshl_add_u64 v[4:5], v[118:119], 0, v[112:113]
	v_fma_f32 v38, -v2, v19, v3
	v_lshl_add_u64 v[22:23], v[116:117], 0, v[112:113]
	global_load_dwordx4 v[0:3], v[4:5], off offset:16
	global_load_dwordx4 v[26:29], v[4:5], off
	s_nop 0
	global_load_dwordx4 v[4:7], v[22:23], off offset:16
	global_load_dwordx4 v[30:33], v[22:23], off
	v_mov_b32_e32 v21, v16
	v_pk_mul_f32 v[8:9], v[8:9], v[20:21]
	v_xor_b32_e32 v13, v14, v13
	v_add_f32_e32 v21, v8, v9
	v_div_scale_f32 v8, s[4:5], v25, v25, v21
	v_rcp_f32_e32 v22, v8
	v_div_fmas_f32 v9, v38, v34, v19
	v_div_fixup_f32 v20, v9, v25, v17
	v_mov_b32_e32 v14, v11
	v_fma_f32 v9, -v8, v22, 1.0
	v_fmac_f32_e32 v22, v9, v22
	v_div_scale_f32 v9, vcc, v21, v25, v21
	v_mul_f32_e32 v17, v9, v22
	v_fma_f32 v19, -v8, v17, v9
	v_fmac_f32_e32 v17, v19, v22
	v_fma_f32 v23, -v8, v17, v9
	v_mul_f32_e32 v8, v18, v18
	v_fmamk_f32 v9, v8, 0xb94c1982, v162
	v_fmaak_f32 v9, v8, v9, 0xbe2aaa9d
	v_mul_f32_e32 v9, v8, v9
	v_fmac_f32_e32 v18, v18, v9
	v_fmamk_f32 v9, v8, 0x37d75334, v161
	v_fmaak_f32 v9, v8, v9, 0x3d2aabf7
	v_fmaak_f32 v9, v8, v9, 0xbf000004
	v_fma_f32 v8, v8, v9, 1.0
	v_and_b32_e32 v9, 1, v15
	v_cmp_eq_u32_e64 s[4:5], 0, v9
	v_lshlrev_b32_e32 v9, 30, v15
	v_and_b32_e32 v9, 0x80000000, v9
	v_cndmask_b32_e64 v8, v8, v18, s[4:5]
	v_xor_b32_e32 v9, v13, v9
	v_xor_b32_e32 v8, v9, v8
	v_cndmask_b32_e64 v8, v168, v8, s[2:3]
	v_mul_f32_e32 v19, v24, v8
	v_fma_f32 v18, v24, v35, -1.0
	v_pk_mul_f32 v[8:9], v[10:11], v[18:19]
	v_mul_f32_e32 v36, v24, v35
	v_add_f32_e32 v13, v8, v9
	v_mov_b32_e32 v8, v19
	v_mov_b32_e32 v9, v10
	v_pk_mul_f32 v[8:9], v[10:11], v[8:9] op_sel_hi:[0,1]
	v_mov_b32_e32 v10, v18
	v_pk_mul_f32 v[10:11], v[14:15], v[10:11] op_sel_hi:[0,1]
	v_add_f32_e32 v9, v9, v11
	v_div_scale_f32 v11, s[2:3], v9, v9, v13
	v_rcp_f32_e32 v14, v11
	v_div_fmas_f32 v15, v23, v22, v17
	v_div_fixup_f32 v24, v15, v25, v21
	v_sub_f32_e32 v8, v8, v10
	v_fma_f32 v15, -v11, v14, 1.0
	v_fmac_f32_e32 v14, v15, v14
	v_div_scale_f32 v15, vcc, v13, v9, v13
	v_mul_f32_e32 v17, v15, v14
	v_fma_f32 v18, -v11, v17, v15
	v_fmac_f32_e32 v17, v18, v14
	v_div_scale_f32 v10, s[2:3], v9, v9, v8
	v_fma_f32 v11, -v11, v17, v15
	v_rcp_f32_e32 v15, v10
	v_div_fmas_f32 v11, v11, v14, v17
	v_div_fixup_f32 v18, v11, v9, v13
	v_lshl_or_b32 v112, v12, 6, v169
	v_fma_f32 v11, -v10, v15, 1.0
	v_fmac_f32_e32 v15, v11, v15
	v_div_scale_f32 v11, vcc, v8, v9, v8
	v_mul_f32_e32 v13, v11, v15
	v_fma_f32 v14, -v10, v13, v11
	v_fmac_f32_e32 v13, v14, v15
	v_fma_f32 v10, -v10, v13, v11
	v_div_fmas_f32 v10, v10, v15, v13
	v_div_fixup_f32 v22, v10, v9, v8
	v_lshlrev_b32_e32 v17, 2, v123
	s_waitcnt vmcnt(2)
; __device__ __forceinline__ unsigned pk2(float lo, float hi) { f32x2 v; v.x = lo; v.y = hi; return __builtin_bit_cast(unsigned, __builtin_convertvector(v, hwbf2)); }
; __device__ __forceinline__ void s5_consts(const Args& a, int g, int lane, S5Consts& c) {
;     ...
;         for (int j = 0; j < 8; ++j) v[j] = (nb & 1) ? (qr * bi[j] + qi * br[j]) : (qr * br[j] - qi * bi[j]);
;         u32x4 w; w.x = pk2(v[0], v[1]); w.y = pk2(v[2], v[3]); w.z = pk2(v[4], v[5]); w.w = pk2(v[6], v[7]);
;         c.bb[nb] = __builtin_bit_cast(bf16x8, w);
; __device__ __forceinline__ void s5_passC_run(const Args& a, LAS unsigned char* wlds, int row0, int nblk, int g, int lane, float& hr, float& hi) {
;     S5Consts c; s5_consts(a, g, lane, c);
;     const int r16 = lane & 15, q4 = lane >> 4;
;     bf16x8 ca[4];
; #pragma unroll
;     for (int kb = 0; kb < 4; ++kb) { float v[8];
; #pragma unroll
;         for (int j = 0; j < 8; ++j) { const int comp = 32 * kb + 8 * q4 + j, p = comp >> 1; v[j] = (comp & 1) ? -a.in[I_CIM][(size_t)(g * 16 + r16) * 64 + p] : a.in[I_CRE][(size_t)(g * 16 + r16) * 64 + p]; }
;         u32x4 w; w.x = pk2(v[0], v[1]); w.y = pk2(v[2], v[3]); w.z = pk2(v[4], v[5]); w.w = pk2(v[6], v[7]); ca[kb] = __builtin_bit_cast(bf16x8, w); }
;     bf16x4 ga[2];
; #pragma unroll
;     for (int mb = 0; mb < 2; ++mb) { float v[4];
; #pragma unroll
;         for (int j = 0; j < 4; ++j) v[j] = a.in[I_GLUW][(size_t)(g * 16 + 4 * q4 + j) * 32 + mb * 16 + r16];
;         u32x2 w; w.x = pk2(v[0], v[1]); w.y = pk2(v[2], v[3]); ga[mb] = __builtin_bit_cast(bf16x4, w); }
;     f32x4 dD, gb0, gb1;
; #pragma unroll
;     for (int j = 0; j < 4; ++j) { dD[j] = a.in[I_S5D][g * 16 + 4 * q4 + j]; gb0[j] = a.in[I_GLUB][g * 32 + 4 * q4 + j]; gb1[j] = a.in[I_GLUB][g * 32 + 16 + 4 * q4 + j]; }
;     const bf16_t* proj = (const bf16_t*)(a.ws + WS_PROJ);
;     bf16_t* mixin = (bf16_t*)(a.ws + WS_MIXIN);
;     const bf16_t* up_ = proj + (size_t)(row0 + (lane & 31)) * NPROJ + 1536 + g * 16 + 8 * (lane >> 5);
;     bf16x8 uf = *(const bf16x8*)up_;
;     u32x2 uus[2], uun[2];
; #pragma unroll
;     for (int sb = 0; sb < 2; ++sb) uus[sb] = *(const u32x2*)(proj + (size_t)(row0 + sb * 16 + r16) * NPROJ + 1536 + g * 16 + 4 * q4);
	v_pk_mul_f32 v[8:9], v[20:21], v[26:27] op_sel_hi:[0,1]
	v_pk_mul_f32 v[26:27], v[24:25], v[26:27] op_sel_hi:[0,1]
	s_waitcnt vmcnt(0)
	v_pk_fma_f32 v[42:43], v[24:25], v[30:31], v[8:9] op_sel_hi:[0,1,1] neg_lo:[0,0,1] neg_hi:[0,0,1]
	v_pk_fma_f32 v[30:31], v[20:21], v[30:31], v[26:27] op_sel_hi:[0,1,1]
	v_pk_mul_f32 v[26:27], v[20:21], v[28:29] op_sel_hi:[0,1]
	v_pk_fma_f32 v[26:27], v[24:25], v[32:33], v[26:27] op_sel_hi:[0,1,1] neg_lo:[0,0,1] neg_hi:[0,0,1]
	v_lshl_add_u64 v[38:39], v[116:117], 0, v[112:113]
	v_lshl_add_u64 v[12:13], v[118:119], 0, v[112:113]
	v_cvt_pk_bf16_f32 v65, v26, v27
	v_pk_mul_f32 v[26:27], v[24:25], v[28:29] op_sel_hi:[0,1]
	v_lshl_or_b32 v17, s8, 12, v17
	v_readlane_b32 s67, v254, 54
	v_readlane_b32 s68, v254, 55
	v_readlane_b32 s69, v254, 56
	v_readlane_b32 s70, v254, 57
	v_readlane_b32 s71, v254, 58
	s_mov_b64 s[44:45], s[64:65]
	s_lshl_b32 s2, s8, 4
	v_cndmask_b32_e64 v132, v36, v37, s[0:1]
	global_load_dwordx4 v[8:11], v[12:13], off offset:16
	global_load_dwordx4 v[34:37], v[12:13], off
	s_nop 0
	global_load_dwordx4 v[12:15], v[38:39], off offset:16
	s_nop 0
	global_load_dwordx4 v[38:41], v[38:39], off
	v_cvt_pk_bf16_f32 v64, v42, v43
	v_pk_fma_f32 v[46:47], v[20:21], v[32:33], v[26:27] op_sel_hi:[0,1,1]
	s_mov_b64 s[46:47], s[66:67]
	global_load_dwordx4 v[26:29], v17, s[44:45]
	global_load_dwordx4 v[42:45], v17, s[46:47]
	global_load_dwordx4 v[50:53], v17, s[44:45] offset:64
	global_load_dwordx4 v[54:57], v17, s[46:47] offset:64
	global_load_dwordx4 v[58:61], v17, s[44:45] offset:128
	global_load_dwordx4 v[104:107], v17, s[46:47] offset:128
	global_load_dwordx4 v[108:111], v17, s[44:45] offset:192
	global_load_dwordx4 v[138:141], v17, s[46:47] offset:192
	v_or_b32_e32 v17, s2, v120
	v_lshlrev_b32_e32 v21, 5, v17
	v_or_b32_e32 v23, v21, v121
	v_readlane_b32 s57, v254, 44
	v_readlane_b32 s58, v254, 45
	v_readlane_b32 s59, v254, 46
	v_readlane_b32 s60, v254, 47
	v_readlane_b32 s61, v254, 48
	v_readlane_b32 s62, v254, 49
	v_readlane_b32 s63, v254, 50
	v_lshlrev_b32_e32 v23, 2, v23
	v_or_b32_e32 v21, v21, v158
	s_lshl_b32 s8, s8, 5
	s_mov_b64 s[48:49], s[68:69]
	s_mov_b64 s[50:51], s[70:71]
	v_or_b32_e32 v25, 0x100, v23
	v_lshlrev_b32_e32 v21, 2, v21
	v_or_b32_e32 v32, s8, v120
	v_readlane_b32 s56, v254, 23
	global_load_dword v131, v23, s[50:51]
	global_load_dword v133, v23, s[50:51] offset:128
	global_load_dword v142, v25, s[50:51]
	global_load_dword v143, v21, s[50:51] offset:128
	s_nop 0
	global_load_dword v21, v21, s[50:51] offset:384
	s_nop 0
	global_load_dword v25, v25, s[50:51] offset:64
	s_nop 0
	global_load_dword v144, v23, s[50:51] offset:384
	s_nop 0
	global_load_dword v23, v23, s[50:51] offset:64
	v_lshlrev_b32_e32 v17, 2, v17
	v_lshlrev_b32_e32 v32, 2, v32
	v_readlane_b32 s57, v254, 24
	global_load_dwordx4 v[68:71], v17, s[48:49]
	s_nop 3
	global_load_dwordx4 v[72:75], v32, s[56:57]
	global_load_dwordx4 v[76:79], v32, s[56:57] offset:64
	v_or_b32_e32 v32, s7, v115
	v_ashrrev_i32_e32 v33, 31, v32
	v_lshlrev_b64 v[32:33], 12, v[32:33]
	v_or_b32_e32 v136, s7, v121
	v_lshl_add_u64 v[32:33], s[10:11], 0, v[32:33]
	v_or_b32_e32 v48, 16, v136
	v_lshl_add_u64 v[32:33], v[32:33], 0, s[8:9]
	v_lshlrev_b32_e32 v112, 1, v114
	v_ashrrev_i32_e32 v137, 31, v136
	v_ashrrev_i32_e32 v49, 31, v48
	v_lshl_add_u64 v[134:135], v[32:33], 0, v[112:113]
	v_lshlrev_b64 v[32:33], 12, v[136:137]
	v_lshlrev_b64 v[48:49], 12, v[48:49]
	v_lshl_add_u64 v[32:33], s[10:11], 0, v[32:33]
	v_lshl_add_u64 v[48:49], s[10:11], 0, v[48:49]
	v_lshl_add_u64 v[32:33], v[32:33], 0, s[8:9]
	v_lshlrev_b32_e32 v112, 1, v120
	v_lshl_add_u64 v[48:49], v[48:49], 0, s[8:9]
	v_lshl_add_u64 v[32:33], v[32:33], 0, v[112:113]
	v_lshl_add_u64 v[48:49], v[48:49], 0, v[112:113]
	global_load_dwordx4 v[88:91], v[134:135], off offset:3072
	s_nop 0
	global_load_dwordx2 v[32:33], v[32:33], off offset:3072
	s_nop 0
	global_load_dwordx2 v[48:49], v[48:49], off offset:3072
	s_mov_b32 s6, 0
	v_cvt_pk_bf16_f32 v80, v30, v31
	v_cvt_pk_bf16_f32 v81, v46, v47
	s_lshl_b32 s2, s2, 1
	v_readlane_b32 s58, v254, 25
	v_readlane_b32 s59, v254, 26
	v_readlane_b32 s60, v254, 27
	v_readlane_b32 s61, v254, 28
	v_readlane_b32 s62, v254, 29
	v_readlane_b32 s63, v254, 30
	v_readlane_b32 s64, v254, 31
	v_readlane_b32 s65, v254, 32
	v_readlane_b32 s66, v254, 33
	v_readlane_b32 s67, v254, 34
	v_readlane_b32 s68, v254, 35
	v_readlane_b32 s69, v254, 36
	v_readlane_b32 s70, v254, 37
	v_readlane_b32 s71, v254, 38
	s_waitcnt vmcnt(9)
	v_pk_mul_f32 v[62:63], v[20:21], v[0:1] op_sel_hi:[0,1]
	s_waitcnt vmcnt(8)
	v_pk_mul_f32 v[0:1], v[24:25], v[0:1] op_sel_hi:[0,1]
	v_pk_fma_f32 v[62:63], v[24:25], v[4:5], v[62:63] op_sel_hi:[0,1,1] neg_lo:[0,0,1] neg_hi:[0,0,1]
	v_pk_fma_f32 v[0:1], v[20:21], v[4:5], v[0:1] op_sel_hi:[0,1,1]
	v_pk_mul_f32 v[4:5], v[20:21], v[2:3] op_sel_hi:[0,1]
	v_pk_mul_f32 v[2:3], v[24:25], v[2:3] op_sel_hi:[0,1]
	v_pk_fma_f32 v[2:3], v[20:21], v[6:7], v[2:3] op_sel_hi:[0,1,1]
	v_cvt_pk_bf16_f32 v82, v0, v1
	v_cvt_pk_bf16_f32 v83, v2, v3
	s_waitcnt vmcnt(6)
; template <bool STORE>
; __device__ __forceinline__ void s5_block(const Args& a, const S5Consts& c, const bf16x8 uf, int lane, float& hr, float& hi, LAS unsigned char* wl, const bf16_t* nxt, bf16x8& nuf) {
;     ...
;     for (int nb = 0; nb < 4; ++nb) bu[nb] = MFMA32(uf, c.bb[nb], zero16());
;     asm volatile("" ::: "memory");
;     nuf = *(const bf16x8*)nxt;
;     asm volatile("" ::: "memory");
; #pragma unroll
; __device__ __forceinline__ void s5_passC_run(const Args& a, LAS unsigned char* wlds, int row0, int nblk, int g, int lane, float& hr, float& hi) {
;     ...
;     for (int kb = 0; kb < 4; ++kb) { float v[8];
; #pragma unroll
;         for (int j = 0; j < 8; ++j) { const int comp = 32 * kb + 8 * q4 + j, p = comp >> 1; v[j] = (comp & 1) ? -a.in[I_CIM][(size_t)(g * 16 + r16) * 64 + p] : a.in[I_CRE][(size_t)(g * 16 + r16) * 64 + p]; }
;         u32x4 w; w.x = pk2(v[0], v[1]); w.y = pk2(v[2], v[3]); w.z = pk2(v[4], v[5]); w.w = pk2(v[6], v[7]); ca[kb] = __builtin_bit_cast(bf16x8, w); }
;     bf16x4 ga[2];
; #pragma unroll
;     for (int mb = 0; mb < 2; ++mb) { float v[4];
; #pragma unroll
;         for (int j = 0; j < 4; ++j) v[j] = a.in[I_GLUW][(size_t)(g * 16 + 4 * q4 + j) * 32 + mb * 16 + r16];
;         u32x2 w; w.x = pk2(v[0], v[1]); w.y = pk2(v[2], v[3]); ga[mb] = __builtin_bit_cast(bf16x4, w); }
;     f32x4 dD, gb0, gb1;
; #pragma unroll
;     for (int j = 0; j < 4; ++j) { dD[j] = a.in[I_S5D][g * 16 + 4 * q4 + j]; gb0[j] = a.in[I_GLUB][g * 32 + 4 * q4 + j]; gb1[j] = a.in[I_GLUB][g * 32 + 16 + 4 * q4 + j]; }
;     const bf16_t* proj = (const bf16_t*)(a.ws + WS_PROJ);
;     bf16_t* mixin = (bf16_t*)(a.ws + WS_MIXIN);
;     const bf16_t* up_ = proj + (size_t)(row0 + (lane & 31)) * NPROJ + 1536 + g * 16 + 8 * (lane >> 5);
;     bf16x8 uf = *(const bf16x8*)up_;
;     u32x2 uus[2], uun[2];
; #pragma unroll
;     for (int sb = 0; sb < 2; ++sb) uus[sb] = *(const u32x2*)(proj + (size_t)(row0 + sb * 16 + r16) * NPROJ + 1536 + g * 16 + 4 * q4);
;     for (int blk = 0; blk < nblk; ++blk) {
;         const int rb = row0 + blk * 32;
;         const int nb = blk < nblk - 1 ? blk + 1 : blk; bf16x8 nuf;
;         s5_block<true>(a, c, uf, lane, hr, hi, wlds, up_ + (size_t)nb * 32 * NPROJ, nuf); uf = nuf;
; #pragma unroll
;         for (int sb = 0; sb < 2; ++sb) uun[sb] = *(const u32x2*)(proj + (size_t)(row0 + nb * 32 + sb * 16 + r16) * NPROJ + 1536 + g * 16 + 4 * q4);
	v_pk_mul_f32 v[0:1], v[22:23], v[34:35] op_sel_hi:[0,1]
	v_pk_mul_f32 v[2:3], v[22:23], v[36:37] op_sel_hi:[0,1]
	v_pk_fma_f32 v[0:1], v[18:19], v[38:39], v[0:1] op_sel_hi:[0,1,1] neg_lo:[0,0,1] neg_hi:[0,0,1]
	v_pk_fma_f32 v[2:3], v[18:19], v[40:41], v[2:3] op_sel_hi:[0,1,1] neg_lo:[0,0,1] neg_hi:[0,0,1]
	v_cvt_pk_bf16_f32 v84, v0, v1
	v_pk_mul_f32 v[0:1], v[18:19], v[34:35] op_sel_hi:[0,1]
	v_cvt_pk_bf16_f32 v85, v2, v3
	v_pk_mul_f32 v[2:3], v[18:19], v[36:37] op_sel_hi:[0,1]
	v_pk_fma_f32 v[4:5], v[24:25], v[6:7], v[4:5] op_sel_hi:[0,1,1] neg_lo:[0,0,1] neg_hi:[0,0,1]
	v_pk_fma_f32 v[0:1], v[22:23], v[38:39], v[0:1] op_sel_hi:[0,1,1]
	v_pk_fma_f32 v[2:3], v[22:23], v[40:41], v[2:3] op_sel_hi:[0,1,1]
	v_cvt_pk_bf16_f32 v67, v4, v5
	v_pk_mul_f32 v[4:5], v[22:23], v[8:9] op_sel_hi:[0,1]
	v_pk_mul_f32 v[6:7], v[22:23], v[10:11] op_sel_hi:[0,1]
	v_cvt_pk_bf16_f32 v92, v0, v1
	v_cvt_pk_bf16_f32 v93, v2, v3
	v_xor_b32_e32 v0, 0x80000000, v42
	v_xor_b32_e32 v1, 0x80000000, v43
	v_xor_b32_e32 v2, 0x80000000, v44
	v_xor_b32_e32 v3, 0x80000000, v45
	v_pk_fma_f32 v[4:5], v[18:19], v[12:13], v[4:5] op_sel_hi:[0,1,1] neg_lo:[0,0,1] neg_hi:[0,0,1]
	v_pk_fma_f32 v[6:7], v[18:19], v[14:15], v[6:7] op_sel_hi:[0,1,1] neg_lo:[0,0,1] neg_hi:[0,0,1]
	v_cvt_pk_bf16_f32 v96, v26, v0
	v_cvt_pk_bf16_f32 v97, v27, v1
	v_cvt_pk_bf16_f32 v98, v28, v2
	v_cvt_pk_bf16_f32 v99, v29, v3
	v_xor_b32_e32 v0, 0x80000000, v54
	v_xor_b32_e32 v1, 0x80000000, v55
	v_xor_b32_e32 v2, 0x80000000, v56
	v_xor_b32_e32 v3, 0x80000000, v57
	v_cvt_pk_bf16_f32 v86, v4, v5
	v_pk_mul_f32 v[4:5], v[18:19], v[8:9] op_sel_hi:[0,1]
	v_cvt_pk_bf16_f32 v87, v6, v7
	v_pk_mul_f32 v[6:7], v[18:19], v[10:11] op_sel_hi:[0,1]
	v_cvt_pk_bf16_f32 v100, v50, v0
	v_cvt_pk_bf16_f32 v101, v51, v1
	v_cvt_pk_bf16_f32 v102, v52, v2
	v_cvt_pk_bf16_f32 v103, v53, v3
	v_xor_b32_e32 v0, 0x80000000, v104
	v_xor_b32_e32 v1, 0x80000000, v105
	v_xor_b32_e32 v2, 0x80000000, v106
	v_xor_b32_e32 v3, 0x80000000, v107
	v_pk_fma_f32 v[4:5], v[22:23], v[12:13], v[4:5] op_sel_hi:[0,1,1]
	v_pk_fma_f32 v[6:7], v[22:23], v[14:15], v[6:7] op_sel_hi:[0,1,1]
	v_cvt_pk_bf16_f32 v104, v58, v0
	v_cvt_pk_bf16_f32 v105, v59, v1
	v_cvt_pk_bf16_f32 v106, v60, v2
	v_cvt_pk_bf16_f32 v107, v61, v3
	v_xor_b32_e32 v0, 0x80000000, v138
	v_xor_b32_e32 v1, 0x80000000, v139
	v_xor_b32_e32 v2, 0x80000000, v140
	v_xor_b32_e32 v3, 0x80000000, v141
	v_cvt_pk_bf16_f32 v139, v142, v144
	v_cndmask_b32_e64 v142, v19, v16, s[0:1]
	v_cvt_pk_bf16_f32 v66, v62, v63
	v_cvt_pk_bf16_f32 v94, v4, v5
	v_cvt_pk_bf16_f32 v95, v6, v7
	v_cvt_pk_bf16_f32 v108, v108, v0
	v_cvt_pk_bf16_f32 v109, v109, v1
	v_cvt_pk_bf16_f32 v110, v110, v2
	v_cvt_pk_bf16_f32 v111, v111, v3
	v_cvt_pk_bf16_f32 v138, v131, v133
	v_cvt_pk_bf16_f32 v140, v23, v143
	v_cvt_pk_bf16_f32 v141, v25, v21
	v_xor_b32_e32 v143, 0x80000000, v142
	v_mov_b32_e32 v133, v132
	v_lshl_add_u64 v[144:145], v[126:127], 0, s[8:9]
	s_waitcnt vmcnt(0)
	v_mov_b32_e32 v152, v32
	v_mov_b32_e32 v153, v33
	v_mov_b32_e32 v156, v48
	v_mov_b32_e32 v157, v49
	v_add_u32_e32 v137, s18, v122
	v_add_u32_e32 v174, v159, v160
	v_add_u32_e32 v175, 0x400, v137
	v_add_u32_e32 v178, 0x800, v137
	v_add_u32_e32 v179, 0xc00, v137
	v_add_u32_e32 v180, 0x1000, v137
	v_add_u32_e32 v181, 0x1200, v137
	v_add_u32_e32 v182, 0x1400, v137
	v_add_u32_e32 v183, 0x1600, v137
	v_add_u32_e32 v184, 0x1800, v137
	v_add_u32_e32 v185, 0x1a00, v137
	v_add_u32_e32 v186, 0x1c00, v137
	v_add_u32_e32 v187, 0x1e00, v137
.LBB0_892:
	s_waitcnt vmcnt(2)
	v_mfma_f32_32x32x16_bf16 v[0:15], v[88:91], v[80:83], 0
	v_lshlrev_b32_e32 v150, 16, v156
	v_and_b32_e32 v151, 0xffff0000, v156
	v_lshlrev_b32_e32 v154, 16, v157
	v_and_b32_e32 v155, 0xffff0000, v157
	v_lshlrev_b32_e32 v146, 16, v152
	v_and_b32_e32 v147, 0xffff0000, v152
	v_lshlrev_b32_e32 v148, 16, v153
	v_mfma_f32_32x32x16_bf16 v[48:63], v[88:91], v[92:95], 0
	v_and_b32_e32 v149, 0xffff0000, v153
	s_add_i32 s4, s6, 1
	s_cmp_lt_u32 s6, 31
	v_ashrrev_i32_e32 v131, 31, v130
	s_cselect_b32 s8, s4, s6
	s_lshl_b64 s[6:7], s[8:9], 17
	v_lshl_add_u32 v190, s8, 5, v136
	v_or_b32_e32 v192, 16, v190
	v_ashrrev_i32_e32 v191, 31, v190
	v_ashrrev_i32_e32 v193, 31, v192
	v_lshlrev_b64 v[190:191], 12, v[190:191]
	v_lshlrev_b64 v[192:193], 12, v[192:193]
	v_lshl_add_u64 v[190:191], v[144:145], 0, v[190:191]
	v_lshl_add_u64 v[192:193], v[144:145], 0, v[192:193]
	global_load_dwordx2 v[152:153], v[190:191], off offset:3072
	global_load_dwordx2 v[156:157], v[192:193], off offset:3072
	v_mfma_f32_32x32x16_bf16 v[16:31], v[88:91], v[64:67], 0
	s_nop 4
	v_permlane32_swap_b32_e32 v0, v48
	v_fmac_f32_e32 v0, v142, v129
	v_fmac_f32_e32 v0, v132, v128
	v_permlane32_swap_b32_e32 v1, v49
	v_permlane32_swap_b32_e32 v2, v50
	v_mfma_f32_32x32x16_bf16 v[32:47], v[88:91], v[84:87], 0
	v_permlane32_swap_b32_e32 v3, v51
	v_lshlrev_b64 v[88:89], 11, v[130:131]
	v_lshl_add_u64 v[170:171], s[88:89], 0, v[88:89]
	v_lshl_add_u64 v[88:89], v[134:135], 0, s[6:7]
	global_load_dwordx4 v[88:91], v[88:89], off offset:3072
	s_nop 5
	v_permlane32_swap_b32_e32 v16, v32
	v_permlane32_swap_b32_e32 v17, v33
	v_fma_f32 v16, -v142, v128, v16
	v_fmac_f32_e32 v16, v132, v129
	v_fma_f32 v17, -v142, v0, v17
	v_fmac_f32_e32 v1, v142, v16
	v_fmac_f32_e32 v17, v132, v16
	v_permlane32_swap_b32_e32 v18, v34
	v_fmac_f32_e32 v1, v132, v0
	v_fmac_f32_e32 v2, v142, v17
	v_permlane32_swap_b32_e32 v19, v35
	v_cvt_pk_bf16_f32 v128, v16, v0
	v_fma_f32 v16, -v142, v1, v18
	v_fmac_f32_e32 v2, v132, v1
	v_cvt_pk_bf16_f32 v0, v17, v1
	v_fmac_f32_e32 v16, v132, v17
	v_fma_f32 v1, -v142, v2, v19
	v_fmac_f32_e32 v3, v142, v16
	v_fmac_f32_e32 v1, v132, v16
	v_fmac_f32_e32 v3, v132, v2
; #define LAS __attribute__((address_space(3)))
; __device__ __forceinline__ unsigned pk2(float lo, float hi) { f32x2 v; v.x = lo; v.y = hi; return __builtin_bit_cast(unsigned, __builtin_convertvector(v, hwbf2)); }
; #define MFMA32(a, b, c) __builtin_amdgcn_mfma_f32_32x32x16_bf16((a), (b), (c), 0, 0, 0)
; __device__ __forceinline__ f32x16 zero16() { f32x16 z; for (int i = 0; i < 16; ++i) z[i] = 0.f; return z; }
; template <bool STORE>
; __device__ __forceinline__ void s5_block(const Args& a, const S5Consts& c, const bf16x8 uf, int lane, float& hr, float& hi, LAS unsigned char* wl, const bf16_t* nxt, bf16x8& nuf) {
;     ...
;     for (int nb = 0; nb < 4; ++nb) bu[nb] = MFMA32(uf, c.bb[nb], zero16());
;     asm volatile("" ::: "memory");
;     nuf = *(const bf16x8*)nxt;
;     asm volatile("" ::: "memory");
; #pragma unroll
;     for (int i = 0; i < 16; ++i) {
;         auto s0 = __builtin_amdgcn_permlane32_swap(__float_as_uint(bu[0][i]), __float_as_uint(bu[2][i]), false, false);
;         auto s1 = __builtin_amdgcn_permlane32_swap(__float_as_uint(bu[1][i]), __float_as_uint(bu[3][i]), false, false);
;         bu[0][i] = __uint_as_float(s0[0]); bu[2][i] = __uint_as_float(s0[1]); bu[1][i] = __uint_as_float(s1[0]); bu[3][i] = __uint_as_float(s1[1]);
;     }
;     const float nlbi = -c.lbi;
; #pragma unroll
;     for (int ib = 0; ib < 4; ++ib) {
; #pragma unroll
;         for (int j = 0; j < 4; ++j) { const float nr = __builtin_fmaf(c.lbr, hr, __builtin_fmaf(nlbi, hi, bu[0][4 * ib + j])), ni = __builtin_fmaf(c.lbr, hi, __builtin_fmaf(c.lbi, hr, bu[1][4 * ib + j])); hr = nr; hi = ni; if (STORE) *(LAS unsigned*)(wl + (8 * ib + j) * 272 + lane * 4) = pk2(hr, hi); }
; #pragma unroll
;         for (int j = 0; j < 4; ++j) { const float nr = __builtin_fmaf(c.lbr, hr, __builtin_fmaf(nlbi, hi, bu[2][4 * ib + j])), ni = __builtin_fmaf(c.lbr, hi, __builtin_fmaf(c.lbi, hr, bu[3][4 * ib + j])); hr = nr; hi = ni; if (STORE) *(LAS unsigned*)(wl + (8 * ib + 4 + j) * 272 + lane * 4) = pk2(hr, hi); }
;     }
	v_fmac_f32_e32 v48, v142, v1
	ds_write2_b32 v137, v128, v0 offset1:68
	v_cvt_pk_bf16_f32 v0, v16, v2
	v_fma_f32 v16, -v142, v3, v32
	v_fmac_f32_e32 v48, v132, v3
	v_cvt_pk_bf16_f32 v2, v1, v3
	v_fmac_f32_e32 v16, v132, v1
	v_fma_f32 v1, -v142, v48, v33
	v_fmac_f32_e32 v49, v142, v16
	v_fmac_f32_e32 v1, v132, v16
	v_fmac_f32_e32 v49, v132, v48
	v_fmac_f32_e32 v50, v142, v1
	v_fma_f32 v3, -v142, v49, v34
	v_fmac_f32_e32 v50, v132, v49
	ds_write2_b32 v137, v0, v2 offset0:136 offset1:204
	v_cvt_pk_bf16_f32 v2, v1, v49
	v_fmac_f32_e32 v3, v132, v1
	v_fma_f32 v1, -v142, v50, v35
	v_permlane32_swap_b32_e32 v4, v52
	v_fmac_f32_e32 v51, v142, v3
	v_fmac_f32_e32 v1, v132, v3
	v_permlane32_swap_b32_e32 v20, v36
	v_cvt_pk_bf16_f32 v0, v16, v48
	v_fmac_f32_e32 v51, v132, v50
	v_fmac_f32_e32 v4, v142, v1
	v_permlane32_swap_b32_e32 v21, v37
	ds_write2_b32 v175, v0, v2 offset0:16 offset1:84
	v_cvt_pk_bf16_f32 v0, v3, v50
	v_fma_f32 v3, -v142, v51, v20
	v_fmac_f32_e32 v4, v132, v51
	v_permlane32_swap_b32_e32 v5, v53
	v_cvt_pk_bf16_f32 v2, v1, v51
	v_fmac_f32_e32 v3, v132, v1
	v_fma_f32 v1, -v142, v4, v21
	v_permlane32_swap_b32_e32 v6, v54
	v_fmac_f32_e32 v5, v142, v3
	v_fmac_f32_e32 v1, v132, v3
	v_permlane32_swap_b32_e32 v22, v38
	v_fmac_f32_e32 v5, v132, v4
	v_fmac_f32_e32 v6, v142, v1
	v_permlane32_swap_b32_e32 v23, v39
	ds_write2_b32 v175, v0, v2 offset0:152 offset1:220
	v_cvt_pk_bf16_f32 v0, v3, v4
	v_fma_f32 v3, -v142, v5, v22
	v_fmac_f32_e32 v6, v132, v5
	v_permlane32_swap_b32_e32 v7, v55
	v_cvt_pk_bf16_f32 v2, v1, v5
	v_fmac_f32_e32 v3, v132, v1
	v_fma_f32 v1, -v142, v6, v23
	v_fmac_f32_e32 v7, v142, v3
	v_fmac_f32_e32 v1, v132, v3
	v_fmac_f32_e32 v7, v132, v6
	v_fmac_f32_e32 v52, v142, v1
	ds_write2_b32 v178, v0, v2 offset0:32 offset1:100
	v_cvt_pk_bf16_f32 v0, v3, v6
	v_fma_f32 v3, -v142, v7, v36
	v_fmac_f32_e32 v52, v132, v7
	v_cvt_pk_bf16_f32 v2, v1, v7
	v_fmac_f32_e32 v3, v132, v1
	v_fma_f32 v1, -v142, v52, v37
	v_fmac_f32_e32 v53, v142, v3
	v_fmac_f32_e32 v1, v132, v3
	v_fmac_f32_e32 v53, v132, v52
	v_fmac_f32_e32 v54, v142, v1
	ds_write2_b32 v178, v0, v2 offset0:168 offset1:236
	v_cvt_pk_bf16_f32 v0, v3, v52
	v_fma_f32 v3, -v142, v53, v38
	v_fmac_f32_e32 v54, v132, v53
	v_cvt_pk_bf16_f32 v2, v1, v53
	v_fmac_f32_e32 v3, v132, v1
	v_fma_f32 v1, -v142, v54, v39
	v_permlane32_swap_b32_e32 v8, v56
	v_fmac_f32_e32 v55, v142, v3
	v_fmac_f32_e32 v1, v132, v3
	v_permlane32_swap_b32_e32 v24, v40
	v_fmac_f32_e32 v55, v132, v54
	v_fmac_f32_e32 v8, v142, v1
	v_permlane32_swap_b32_e32 v25, v41
	ds_write2_b32 v179, v0, v2 offset0:48 offset1:116
	v_cvt_pk_bf16_f32 v0, v3, v54
	v_fma_f32 v3, -v142, v55, v24
	v_fmac_f32_e32 v8, v132, v55
	v_permlane32_swap_b32_e32 v9, v57
	v_cvt_pk_bf16_f32 v2, v1, v55
	v_fmac_f32_e32 v3, v132, v1
	v_fma_f32 v1, -v142, v8, v25
	v_permlane32_swap_b32_e32 v10, v58
	v_fmac_f32_e32 v9, v142, v3
	v_fmac_f32_e32 v1, v132, v3
	v_permlane32_swap_b32_e32 v26, v42
	v_fmac_f32_e32 v9, v132, v8
	v_fmac_f32_e32 v10, v142, v1
	v_permlane32_swap_b32_e32 v27, v43
	ds_write2_b32 v179, v0, v2 offset0:184 offset1:252
	v_cvt_pk_bf16_f32 v0, v3, v8
	v_fma_f32 v3, -v142, v9, v26
	v_fmac_f32_e32 v10, v132, v9
	v_add_u32_e32 v188, 16, v130
	v_permlane32_swap_b32_e32 v11, v59
	v_cvt_pk_bf16_f32 v2, v1, v9
	v_fmac_f32_e32 v3, v132, v1
	v_fma_f32 v1, -v142, v10, v27
	v_ashrrev_i32_e32 v189, 31, v188
	v_fmac_f32_e32 v11, v142, v3
	v_fmac_f32_e32 v1, v132, v3
	v_lshlrev_b64 v[172:173], 11, v[188:189]
	v_fmac_f32_e32 v11, v132, v10
	v_fmac_f32_e32 v56, v142, v1
	ds_write2_b32 v180, v0, v2 offset0:64 offset1:132
	v_cvt_pk_bf16_f32 v0, v3, v10
	v_fma_f32 v3, -v142, v11, v40
	v_fmac_f32_e32 v56, v132, v11
	v_cvt_pk_bf16_f32 v2, v1, v11
	v_fmac_f32_e32 v3, v132, v1
	v_fma_f32 v1, -v142, v56, v41
	v_fmac_f32_e32 v57, v142, v3
	v_fmac_f32_e32 v1, v132, v3
	v_fmac_f32_e32 v57, v132, v56
	v_fmac_f32_e32 v58, v142, v1
	ds_write2_b32 v181, v0, v2 offset0:72 offset1:140
	v_cvt_pk_bf16_f32 v0, v3, v56
	v_fma_f32 v3, -v142, v57, v42
	v_fmac_f32_e32 v58, v132, v57
	v_cvt_pk_bf16_f32 v2, v1, v57
	v_fmac_f32_e32 v3, v132, v1
	v_fma_f32 v1, -v142, v58, v43
	v_permlane32_swap_b32_e32 v12, v60
	v_fmac_f32_e32 v59, v142, v3
	v_fmac_f32_e32 v1, v132, v3
	v_permlane32_swap_b32_e32 v28, v44
	v_fmac_f32_e32 v59, v132, v58
	v_fmac_f32_e32 v12, v142, v1
	v_permlane32_swap_b32_e32 v29, v45
	ds_write2_b32 v182, v0, v2 offset0:80 offset1:148
	v_cvt_pk_bf16_f32 v0, v3, v58
	v_fma_f32 v3, -v142, v59, v28
	v_fmac_f32_e32 v12, v132, v59
	v_permlane32_swap_b32_e32 v13, v61
	v_cvt_pk_bf16_f32 v2, v1, v59
	v_fmac_f32_e32 v3, v132, v1
	v_fma_f32 v1, -v142, v12, v29
	v_permlane32_swap_b32_e32 v14, v62
	v_fmac_f32_e32 v13, v142, v3
	v_fmac_f32_e32 v1, v132, v3
	v_permlane32_swap_b32_e32 v30, v46
	v_fmac_f32_e32 v13, v132, v12
	v_fmac_f32_e32 v14, v142, v1
	v_permlane32_swap_b32_e32 v31, v47
	ds_write2_b32 v183, v0, v2 offset0:88 offset1:156
	v_cvt_pk_bf16_f32 v0, v3, v12
	v_fma_f32 v3, -v142, v13, v30
	v_fmac_f32_e32 v14, v132, v13
	v_permlane32_swap_b32_e32 v15, v63
	v_cvt_pk_bf16_f32 v2, v1, v13
	v_fmac_f32_e32 v3, v132, v1
	v_fma_f32 v1, -v142, v14, v31
	v_fmac_f32_e32 v15, v142, v3
	v_fmac_f32_e32 v1, v132, v3
	v_fmac_f32_e32 v15, v132, v14
	v_fmac_f32_e32 v60, v142, v1
	ds_write2_b32 v184, v0, v2 offset0:96 offset1:164
	v_cvt_pk_bf16_f32 v0, v3, v14
	v_cvt_pk_bf16_f32 v2, v1, v15
	v_fma_f32 v3, -v142, v15, v44
	v_fmac_f32_e32 v60, v132, v15
	ds_write2_b32 v185, v0, v2 offset0:104 offset1:172
	v_fmac_f32_e32 v3, v132, v1
	v_fma_f32 v2, -v142, v60, v45
	v_fmac_f32_e32 v61, v142, v3
	v_fmac_f32_e32 v2, v132, v3
	v_fmac_f32_e32 v61, v132, v60
	v_fmac_f32_e32 v62, v142, v2
	v_cvt_pk_bf16_f32 v1, v3, v60
	v_cvt_pk_bf16_f32 v3, v2, v61
	v_fma_f32 v0, -v142, v61, v46
	v_fmac_f32_e32 v62, v132, v61
	v_mov_b32_e32 v46, v63
	ds_write2_b32 v186, v1, v3 offset0:112 offset1:180
	v_fmac_f32_e32 v0, v132, v2
	v_mov_b32_e32 v1, v62
	v_cvt_pk_bf16_f32 v2, v0, v62
	v_mov_b32_e32 v63, v0
	v_pk_fma_f32 v[0:1], v[142:143], v[0:1], v[46:47]
	v_pk_fma_f32 v[128:129], v[132:133], v[62:63], v[0:1]
	v_cvt_pk_bf16_f32 v0, v129, v128
	ds_write2_b32 v187, v2, v0 offset0:120 offset1:188
	s_waitcnt lgkmcnt(0)
; #define LAS __attribute__((address_space(3)))
; __device__ __forceinline__ float bf2f(unsigned v) { return __uint_as_float(v << 16); }
; __device__ __forceinline__ unsigned pk2(float lo, float hi) { f32x2 v; v.x = lo; v.y = hi; return __builtin_bit_cast(unsigned, __builtin_convertvector(v, hwbf2)); }
; __device__ __forceinline__ void s5_passC_run(const Args& a, LAS unsigned char* wlds, int row0, int nblk, int g, int lane, float& hr, float& hi) {
;     ...
;         for (int sb = 0; sb < 2; ++sb) {
;             f32x4 y = (f32x4){0.f, 0.f, 0.f, 0.f};
; #pragma unroll
;             for (int kb = 0; kb < 4; ++kb) { const bf16x8 hb = *(const LAS bf16x8*)(wlds + (sb * 16 + r16) * S5_LD + (32 * kb + 8 * q4) * 2);
;                 y = __builtin_amdgcn_mfma_f32_16x16x32_bf16(ca[kb], hb, y, 0, 0, 0); }
;             const int row = rb + sb * 16 + r16;
;             const u32x2 uu = uus[sb];
;             const float uv[4] = {bf2f(uu.x & 0xffff), bf2f(uu.x >> 16), bf2f(uu.y & 0xffff), bf2f(uu.y >> 16)};
;             float ge[4];
; #pragma unroll
;             for (int j = 0; j < 4; ++j) ge[j] = gelu_tanh(y[j] + dD[j] * uv[j]);
;             u32x2 gw; gw.x = pk2(ge[0], ge[1]); gw.y = pk2(ge[2], ge[3]);
;             const bf16x4 gbf = __builtin_bit_cast(bf16x4, gw);
;             const f32x4 o0 = __builtin_amdgcn_mfma_f32_16x16x16bf16_1k(ga[0], gbf, gb0, 0, 0, 0);
;             const f32x4 o1 = __builtin_amdgcn_mfma_f32_16x16x16bf16_1k(ga[1], gbf, gb1, 0, 0, 0);
;             float ov[4];
; #pragma unroll
;             for (int j = 0; j < 4; ++j) ov[j] = o0[j] * __builtin_amdgcn_rcpf(1.f + __builtin_amdgcn_exp2f(-1.4426950409f * o1[j]));
;             u32x2 ow; ow.x = pk2(ov[0], ov[1]); ow.y = pk2(ov[2], ov[3]);
;             *(u32x2*)(mixin + (size_t)row * DM + 512 + g * 16 + 4 * q4) = ow;
;         }
;         asm volatile("s_waitcnt lgkmcnt(0)" ::: "memory");
;         uus[0] = uun[0]; uus[1] = uun[1];
	ds_read_b128 v[0:3], v174
	ds_read_b128 v[4:7], v174 offset:64
	ds_read_b128 v[8:11], v174 offset:4352
	ds_read_b128 v[12:15], v174 offset:4416
	s_waitcnt lgkmcnt(3)
	v_mfma_f32_16x16x32_bf16 v[0:3], v[96:99], v[0:3], 0
	s_mov_b32 s3, s9
	v_lshl_add_u64 v[16:17], v[170:171], 0, s[2:3]
	v_lshl_add_u64 v[18:19], s[88:89], 0, v[172:173]
	s_waitcnt lgkmcnt(1)
	v_mfma_f32_16x16x32_bf16 v[8:11], v[96:99], v[8:11], 0
	v_lshl_add_u64 v[20:21], v[16:17], 0, v[112:113]
	v_lshl_add_u64 v[22:23], v[18:19], 0, s[2:3]
	v_add_co_u32_e32 v20, vcc, s55, v20
	v_mfma_f32_16x16x32_bf16 v[0:3], v[100:103], v[4:7], v[0:3]
	s_nop 0
	v_addc_co_u32_e32 v21, vcc, 0, v21, vcc
	v_add_u32_e32 v130, 32, v130
	s_waitcnt lgkmcnt(0)
	v_mfma_f32_16x16x32_bf16 v[4:7], v[100:103], v[12:15], v[8:11]
	s_nop 2
	ds_read_b128 v[8:11], v174 offset:128
	ds_read_b128 v[12:15], v174 offset:192
	s_mov_b32 s6, s4
	s_cmp_eq_u32 s4, 32
	s_waitcnt lgkmcnt(1)
	v_mfma_f32_16x16x32_bf16 v[0:3], v[104:107], v[8:11], v[0:3]
	ds_read_b128 v[8:11], v174 offset:4480
	ds_read_b128 v[16:19], v174 offset:4544
	s_waitcnt lgkmcnt(1)
	v_mfma_f32_16x16x32_bf16 v[4:7], v[104:107], v[8:11], v[4:7]
	v_mfma_f32_16x16x32_bf16 v[0:3], v[108:111], v[12:15], v[0:3]
	v_lshl_add_u64 v[12:13], v[22:23], 0, v[112:113]
	v_add_co_u32_e32 v22, vcc, 0x22c00000, v12
	s_waitcnt lgkmcnt(0)
	v_mfma_f32_16x16x32_bf16 v[4:7], v[108:111], v[16:19], v[4:7]
	v_addc_co_u32_e32 v23, vcc, 0, v13, vcc
	s_nop 2
	v_pk_fma_f32 v[0:1], v[68:69], v[146:147], v[0:1]
	v_pk_fma_f32 v[2:3], v[70:71], v[148:149], v[2:3]
	s_nop 0
	v_pk_mul_f32 v[10:11], v[2:3], v[2:3]
	v_pk_fma_f32 v[4:5], v[68:69], v[150:151], v[4:5]
	v_pk_fma_f32 v[8:9], v[70:71], v[154:155], v[6:7]
	v_pk_mul_f32 v[6:7], v[0:1], v[0:1]
	v_pk_mul_f32 v[14:15], v[4:5], v[4:5]
	v_pk_mul_f32 v[16:17], v[8:9], v[8:9]
	v_fmamk_f32 v6, v6, 0xbdd2d3e2, v163
	v_fmamk_f32 v7, v7, 0xbdd2d3e2, v163
	v_fmamk_f32 v10, v10, 0xbdd2d3e2, v163
	v_fmamk_f32 v11, v11, 0xbdd2d3e2, v163
	v_fmamk_f32 v12, v14, 0xbdd2d3e2, v163
	v_fmamk_f32 v14, v15, 0xbdd2d3e2, v163
	v_fmamk_f32 v15, v16, 0xbdd2d3e2, v163
	v_fmamk_f32 v16, v17, 0xbdd2d3e2, v163
	v_mul_f32_e32 v6, v0, v6
	v_mul_f32_e32 v7, v1, v7
	v_mul_f32_e32 v10, v2, v10
	v_mul_f32_e32 v11, v3, v11
	v_mul_f32_e32 v12, v4, v12
	v_mul_f32_e32 v14, v5, v14
	v_mul_f32_e32 v15, v8, v15
	v_mul_f32_e32 v16, v9, v16
	v_exp_f32_e32 v6, v6
	v_exp_f32_e32 v7, v7
	v_exp_f32_e32 v10, v10
	v_exp_f32_e32 v11, v11
	v_exp_f32_e32 v12, v12
	v_exp_f32_e32 v14, v14
	v_exp_f32_e32 v15, v15
	v_exp_f32_e32 v16, v16
	v_add_f32_e32 v6, 1.0, v6
	v_add_f32_e32 v7, 1.0, v7
	v_add_f32_e32 v10, 1.0, v10
	v_add_f32_e32 v11, 1.0, v11
	v_add_f32_e32 v12, 1.0, v12
	v_add_f32_e32 v17, 1.0, v14
	v_add_f32_e32 v18, 1.0, v15
	v_add_f32_e32 v19, 1.0, v16
	v_rcp_f32_e32 v6, v6
	v_rcp_f32_e32 v7, v7
	v_rcp_f32_e32 v10, v10
	v_rcp_f32_e32 v11, v11
	v_rcp_f32_e32 v14, v12
	v_rcp_f32_e32 v15, v17
	v_rcp_f32_e32 v16, v18
	v_rcp_f32_e32 v17, v19
	v_pk_mul_f32 v[0:1], v[0:1], v[6:7]
	v_pk_mul_f32 v[2:3], v[2:3], v[10:11]
	v_cvt_pk_bf16_f32 v6, v0, v1
	v_cvt_pk_bf16_f32 v7, v2, v3
	v_pk_mul_f32 v[10:11], v[4:5], v[14:15]
	v_pk_mul_f32 v[8:9], v[8:9], v[16:17]
	v_mfma_f32_16x16x16_bf16 v[0:3], v[138:139], v[6:7], v[72:75]
	v_cvt_pk_bf16_f32 v14, v10, v11
	v_cvt_pk_bf16_f32 v15, v8, v9
	v_mfma_f32_16x16x16_bf16 v[4:7], v[140:141], v[6:7], v[76:79]
	s_nop 0
	v_mfma_f32_16x16x16_bf16 v[8:11], v[138:139], v[14:15], v[72:75]
	v_mfma_f32_16x16x16_bf16 v[12:15], v[140:141], v[14:15], v[76:79]
	s_nop 4
	v_mul_f32_e32 v4, 0xbfb8aa3b, v4
	v_mul_f32_e32 v5, 0xbfb8aa3b, v5
	v_mul_f32_e32 v6, 0xbfb8aa3b, v6
	v_mul_f32_e32 v7, 0xbfb8aa3b, v7
	v_exp_f32_e32 v4, v4
	v_mul_f32_e32 v12, 0xbfb8aa3b, v12
	v_mul_f32_e32 v13, 0xbfb8aa3b, v13
	v_mul_f32_e32 v14, 0xbfb8aa3b, v14
	v_mul_f32_e32 v15, 0xbfb8aa3b, v15
	v_exp_f32_e32 v5, v5
	v_exp_f32_e32 v6, v6
	v_exp_f32_e32 v7, v7
	v_exp_f32_e32 v12, v12
	v_exp_f32_e32 v13, v13
	v_exp_f32_e32 v14, v14
	v_exp_f32_e32 v15, v15
	v_add_f32_e32 v4, 1.0, v4
	v_add_f32_e32 v5, 1.0, v5
	v_add_f32_e32 v6, 1.0, v6
	v_add_f32_e32 v7, 1.0, v7
	v_add_f32_e32 v12, 1.0, v12
	v_add_f32_e32 v13, 1.0, v13
	v_add_f32_e32 v14, 1.0, v14
	v_add_f32_e32 v15, 1.0, v15
	v_rcp_f32_e32 v4, v4
	v_rcp_f32_e32 v5, v5
	v_rcp_f32_e32 v6, v6
	v_rcp_f32_e32 v7, v7
	v_rcp_f32_e32 v12, v12
	v_rcp_f32_e32 v13, v13
	v_rcp_f32_e32 v14, v14
	v_rcp_f32_e32 v15, v15
	v_pk_mul_f32 v[0:1], v[0:1], v[4:5]
	v_pk_mul_f32 v[2:3], v[2:3], v[6:7]
	v_pk_mul_f32 v[4:5], v[8:9], v[12:13]
	v_pk_mul_f32 v[6:7], v[10:11], v[14:15]
	v_cvt_pk_bf16_f32 v0, v0, v1
	v_cvt_pk_bf16_f32 v1, v2, v3
	v_cvt_pk_bf16_f32 v2, v4, v5
	v_cvt_pk_bf16_f32 v3, v6, v7
	global_store_dwordx2 v[20:21], v[0:1], off offset:1024
	global_store_dwordx2 v[22:23], v[2:3], off offset:1024
	s_waitcnt lgkmcnt(0)
	s_cbranch_scc0 .LBB0_892
	s_waitcnt vmcnt(0)
	s_branch .LBB0_855
